# np16 + nt cache policy on the dword loads of the prep phase
# speedup vs baseline: 1.0156x; 1.0001x over previous
.LBB0_32:
	s_or_b64 exec, exec, s[36:37]
	s_waitcnt lgkmcnt(0)
	s_barrier
	global_load_dword v2, v[58:59], off nt
	s_mov_b64 s[36:37], 0
	v_mov_b32_e32 v4, v104
	s_waitcnt vmcnt(0)
	v_mov_b32_e32 v3, v2
.LBB0_33:
	v_lshl_add_u64 v[6:7], v[74:75], 0, s[36:37]
	global_load_dword v8, v[6:7], off nt
	global_load_dword v10, v[6:7], off offset:256 nt
	global_load_dword v12, v[6:7], off offset:512 nt
	global_load_dword v14, v[6:7], off offset:768 nt
	global_load_dword v16, v[6:7], off offset:1024 nt
	global_load_dword v18, v[6:7], off offset:1280 nt
	global_load_dword v20, v[6:7], off offset:1536 nt
	global_load_dword v22, v[6:7], off offset:1792 nt
	global_load_dword v24, v[6:7], off offset:2048 nt
	global_load_dword v26, v[6:7], off offset:2304 nt
	s_nop 0
	global_load_dword v6, v[6:7], off offset:2560 nt
	v_add_u32_e32 v5, 0x500, v4
	ds_read2_b32 v[28:29], v4 offset0:6 offset1:7
	ds_read2_b32 v[30:31], v4 offset0:8 offset1:9
	v_add_u32_e32 v13, 0x520, v4
	ds_read2_b32 v[32:33], v4 offset1:1
	ds_read2_b32 v[34:35], v4 offset0:2 offset1:3
	ds_read2_b32 v[36:37], v4 offset0:4 offset1:5
	ds_read2_b32 v[38:39], v13 offset1:1
	v_add_u32_e32 v7, 0x508, v4
	v_add_u32_e32 v9, 0x510, v4
	v_add_u32_e32 v11, 0x518, v4
	v_add_u32_e32 v15, 40, v4
	ds_read2_b32 v[40:41], v5 offset1:1
	ds_read2_b32 v[42:43], v7 offset1:1
	ds_read2_b32 v[44:45], v9 offset1:1
	ds_read2_b32 v[46:47], v11 offset1:1
	ds_read2st64_b32 v[48:49], v15 offset1:5
	s_waitcnt lgkmcnt(8)
	v_mov_b32_e32 v51, v32
	s_waitcnt lgkmcnt(4)
	v_mov_b32_e32 v50, v40
	v_mov_b32_e32 v32, v41
	v_mov_b32_e32 v53, v34
	s_waitcnt lgkmcnt(3)
	v_mov_b32_e32 v52, v42
	v_mov_b32_e32 v34, v43
	v_mov_b32_e32 v97, v36
	s_waitcnt lgkmcnt(2)
	v_mov_b32_e32 v96, v44
	v_mov_b32_e32 v36, v45
	v_mov_b32_e32 v99, v28
	s_waitcnt lgkmcnt(1)
	v_mov_b32_e32 v98, v46
	v_mov_b32_e32 v28, v47
	v_mov_b32_e32 v127, v30
	v_mov_b32_e32 v126, v38
	s_add_u32 s36, s36, 0xb00
	v_mov_b32_e32 v30, v39
	s_addc_u32 s37, s37, 0
	s_waitcnt lgkmcnt(0)
	v_mov_b32_e32 v38, v49
	v_mov_b32_e32 v39, v48
	v_add_u32_e32 v4, 44, v4
	s_cmpk_eq_i32 s36, 0x2100
	s_waitcnt vmcnt(10)
	v_pk_fma_f32 v[2:3], v[8:9], v[50:51], v[2:3] op_sel_hi:[0,1,1]
	s_waitcnt vmcnt(9)
	v_pk_fma_f32 v[2:3], v[10:11], v[32:33], v[2:3] op_sel_hi:[0,1,1]
	s_waitcnt vmcnt(8)
	v_pk_fma_f32 v[2:3], v[12:13], v[52:53], v[2:3] op_sel_hi:[0,1,1]
	s_waitcnt vmcnt(7)
	v_pk_fma_f32 v[2:3], v[14:15], v[34:35], v[2:3] op_sel_hi:[0,1,1]
	s_waitcnt vmcnt(6)
	v_pk_fma_f32 v[2:3], v[16:17], v[96:97], v[2:3] op_sel_hi:[0,1,1]
	s_waitcnt vmcnt(5)
	v_pk_fma_f32 v[2:3], v[18:19], v[36:37], v[2:3] op_sel_hi:[0,1,1]
	s_waitcnt vmcnt(4)
	v_pk_fma_f32 v[2:3], v[20:21], v[98:99], v[2:3] op_sel_hi:[0,1,1]
	s_waitcnt vmcnt(3)
	v_pk_fma_f32 v[2:3], v[22:23], v[28:29], v[2:3] op_sel_hi:[0,1,1]
	s_waitcnt vmcnt(2)
	v_pk_fma_f32 v[2:3], v[24:25], v[126:127], v[2:3] op_sel_hi:[0,1,1]
	s_waitcnt vmcnt(1)
	v_pk_fma_f32 v[2:3], v[26:27], v[30:31], v[2:3] op_sel_hi:[0,1,1]
	s_waitcnt vmcnt(0)
	v_pk_fma_f32 v[2:3], v[6:7], v[38:39], v[2:3] op_sel_hi:[0,1,1]
	s_cbranch_scc0 .LBB0_33
	global_load_dword v4, v[60:61], off nt
	s_mov_b64 s[36:37], 0
	v_mov_b32_e32 v54, v115
	s_waitcnt vmcnt(0)
	v_mul_f32_e32 v3, v3, v4
	v_mul_f32_e32 v2, v2, v4
	v_mul_f32_e32 v4, 0.15915494, v3
	v_mul_f32_e32 v5, 0.15915494, v2
	v_rndne_f32_e32 v4, v4
	v_rndne_f32_e32 v5, v5
	v_fmac_f32_e32 v3, 0xc0c90fdb, v4
	v_fmac_f32_e32 v2, 0xc0c90fdb, v5
	v_fmac_f32_e32 v3, 0x343bbd2e, v4
	v_fmac_f32_e32 v2, 0x343bbd2e, v5
	v_mul_f32_e32 v3, 0.15915494, v3
	v_mul_f32_e32 v2, 0.15915494, v2
	v_sin_f32_e32 v3, v3
	v_sin_f32_e32 v2, v2
	ds_write_b32 v105, v3 offset:4096
	ds_write_b32 v106, v2 offset:6144
	s_waitcnt lgkmcnt(0)
	s_barrier
	global_load_dword v96, v[62:63], off nt
	s_waitcnt vmcnt(0)
	v_mov_b32_e32 v97, v96
.LBB0_35:
	v_lshl_add_u64 v[98:99], v[76:77], 0, s[36:37]
	ds_read_b128 v[14:17], v54
	ds_read_b128 v[10:13], v54 offset:16
	ds_read_b128 v[6:9], v54 offset:32
	ds_read_b128 v[2:5], v54 offset:48
	ds_read_b128 v[18:21], v54 offset:2048
	ds_read_b128 v[22:25], v54 offset:2064
	ds_read_b128 v[26:29], v54 offset:2080
	ds_read_b128 v[34:37], v54 offset:2096
	ds_read_b128 v[30:33], v54 offset:64
	ds_read_b128 v[38:41], v54 offset:80
	ds_read_b128 v[50:53], v54 offset:2112
	ds_read_b128 v[46:49], v54 offset:2128
	ds_read_b128 v[42:45], v54 offset:96
	ds_read_b128 v[126:129], v54 offset:112
	ds_read_b128 v[130:133], v54 offset:2144
	ds_read_b128 v[134:137], v54 offset:2160
	global_load_dword v138, v[98:99], off nt
	global_load_dword v140, v[98:99], off offset:256 nt
	global_load_dword v142, v[98:99], off offset:512 nt
	global_load_dword v144, v[98:99], off offset:768 nt
	global_load_dword v146, v[98:99], off offset:1024 nt
	global_load_dword v148, v[98:99], off offset:1280 nt
	global_load_dword v150, v[98:99], off offset:1536 nt
	global_load_dword v152, v[98:99], off offset:1792 nt
	global_load_dword v154, v[98:99], off offset:2048 nt
	global_load_dword v156, v[98:99], off offset:2304 nt
	global_load_dword v158, v[98:99], off offset:2560 nt
	global_load_dword v160, v[98:99], off offset:2816 nt
	global_load_dword v162, v[98:99], off offset:3072 nt
	global_load_dword v164, v[98:99], off offset:3328 nt
	global_load_dword v166, v[98:99], off offset:3584 nt
	global_load_dword v168, v[98:99], off offset:3840 nt
	v_add_co_u32_e32 v98, vcc, s56, v98
	s_waitcnt lgkmcnt(11)
	v_mov_b32_e32 v186, v18
	v_addc_co_u32_e32 v99, vcc, 0, v99, vcc
	global_load_dword v170, v[98:99], off nt
	global_load_dword v172, v[98:99], off offset:256 nt
	global_load_dword v174, v[98:99], off offset:512 nt
	global_load_dword v176, v[98:99], off offset:768 nt
	global_load_dword v178, v[98:99], off offset:1024 nt
	global_load_dword v180, v[98:99], off offset:1280 nt
	global_load_dword v182, v[98:99], off offset:1536 nt
	global_load_dword v184, v[98:99], off offset:1792 nt
	v_mov_b32_e32 v18, v20
	s_waitcnt lgkmcnt(10)
	v_mov_b32_e32 v20, v22
	v_mov_b32_e32 v22, v24
	s_waitcnt lgkmcnt(9)
	v_mov_b32_e32 v24, v26
	v_mov_b32_e32 v26, v28
	s_waitcnt lgkmcnt(8)
	v_mov_b32_e32 v28, v34
	v_mov_b32_e32 v34, v36
	s_waitcnt lgkmcnt(5)
	v_mov_b32_e32 v36, v50
	v_mov_b32_e32 v50, v52
	s_waitcnt lgkmcnt(4)
	v_mov_b32_e32 v52, v46
	v_mov_b32_e32 v46, v48
	s_waitcnt lgkmcnt(1)
	v_mov_b32_e32 v48, v130
	v_mov_b32_e32 v130, v132
	s_waitcnt lgkmcnt(0)
	v_mov_b32_e32 v132, v134
	v_mov_b32_e32 v134, v136
	global_load_dword v136, v[98:99], off offset:2048 nt
	global_load_dword v188, v[98:99], off offset:2304 nt
	v_mov_b32_e32 v187, v14
	v_mov_b32_e32 v14, v19
	v_mov_b32_e32 v19, v16
	v_mov_b32_e32 v16, v21
	v_mov_b32_e32 v21, v10
	v_mov_b32_e32 v10, v23
	v_mov_b32_e32 v23, v12
	v_mov_b32_e32 v12, v25
	v_mov_b32_e32 v25, v6
	v_mov_b32_e32 v6, v27
	v_mov_b32_e32 v27, v8
	v_mov_b32_e32 v8, v29
	v_mov_b32_e32 v29, v2
	v_mov_b32_e32 v2, v35
	v_mov_b32_e32 v35, v4
	v_mov_b32_e32 v4, v37
	v_mov_b32_e32 v37, v30
	v_mov_b32_e32 v30, v51
	v_mov_b32_e32 v51, v32
	v_mov_b32_e32 v32, v53
	v_mov_b32_e32 v53, v38
	v_mov_b32_e32 v38, v47
	v_mov_b32_e32 v47, v40
	v_mov_b32_e32 v40, v49
	v_mov_b32_e32 v49, v42
	v_mov_b32_e32 v42, v131
	v_mov_b32_e32 v131, v44
	v_mov_b32_e32 v44, v133
	v_mov_b32_e32 v133, v126
	v_mov_b32_e32 v126, v135
	v_mov_b32_e32 v135, v128
	s_add_u32 s36, s36, 0x2000
	v_mov_b32_e32 v128, v137
	s_addc_u32 s37, s37, 0
	v_add_u32_e32 v54, 0x80, v54
	s_cmpk_eq_i32 s36, 0x4000
	s_waitcnt vmcnt(25)
	v_pk_fma_f32 v[96:97], v[138:139], v[186:187], v[96:97] op_sel_hi:[0,1,1]
	global_load_dword v138, v[98:99], off offset:2560 nt
	global_load_dword v186, v[98:99], off offset:2816 nt
	s_waitcnt vmcnt(26)
	v_pk_fma_f32 v[14:15], v[140:141], v[14:15], v[96:97] op_sel_hi:[0,1,1]
	global_load_dword v96, v[98:99], off offset:3072 nt
	s_waitcnt vmcnt(26)
	v_pk_fma_f32 v[14:15], v[142:143], v[18:19], v[14:15] op_sel_hi:[0,1,1]
	global_load_dword v18, v[98:99], off offset:3328 nt
	global_load_dword v140, v[98:99], off offset:3584 nt
	s_nop 0
	global_load_dword v98, v[98:99], off offset:3840 nt
	s_waitcnt vmcnt(28)
	v_pk_fma_f32 v[14:15], v[144:145], v[16:17], v[14:15] op_sel_hi:[0,1,1]
	s_waitcnt vmcnt(27)
	v_pk_fma_f32 v[14:15], v[146:147], v[20:21], v[14:15] op_sel_hi:[0,1,1]
	s_waitcnt vmcnt(26)
	v_pk_fma_f32 v[10:11], v[148:149], v[10:11], v[14:15] op_sel_hi:[0,1,1]
	s_waitcnt vmcnt(25)
	v_pk_fma_f32 v[10:11], v[150:151], v[22:23], v[10:11] op_sel_hi:[0,1,1]
	s_waitcnt vmcnt(24)
	v_pk_fma_f32 v[10:11], v[152:153], v[12:13], v[10:11] op_sel_hi:[0,1,1]
	s_waitcnt vmcnt(23)
	v_pk_fma_f32 v[10:11], v[154:155], v[24:25], v[10:11] op_sel_hi:[0,1,1]
	s_waitcnt vmcnt(22)
	v_pk_fma_f32 v[6:7], v[156:157], v[6:7], v[10:11] op_sel_hi:[0,1,1]
	s_waitcnt vmcnt(21)
	v_pk_fma_f32 v[6:7], v[158:159], v[26:27], v[6:7] op_sel_hi:[0,1,1]
	s_waitcnt vmcnt(20)
	v_pk_fma_f32 v[6:7], v[160:161], v[8:9], v[6:7] op_sel_hi:[0,1,1]
	s_waitcnt vmcnt(19)
	v_pk_fma_f32 v[6:7], v[162:163], v[28:29], v[6:7] op_sel_hi:[0,1,1]
	s_waitcnt vmcnt(18)
	v_pk_fma_f32 v[2:3], v[164:165], v[2:3], v[6:7] op_sel_hi:[0,1,1]
	s_waitcnt vmcnt(17)
	v_pk_fma_f32 v[2:3], v[166:167], v[34:35], v[2:3] op_sel_hi:[0,1,1]
	s_waitcnt vmcnt(16)
	v_pk_fma_f32 v[2:3], v[168:169], v[4:5], v[2:3] op_sel_hi:[0,1,1]
	s_waitcnt vmcnt(15)
	v_pk_fma_f32 v[2:3], v[170:171], v[36:37], v[2:3] op_sel_hi:[0,1,1]
	s_waitcnt vmcnt(14)
	v_pk_fma_f32 v[2:3], v[172:173], v[30:31], v[2:3] op_sel_hi:[0,1,1]
	s_waitcnt vmcnt(13)
	v_pk_fma_f32 v[2:3], v[174:175], v[50:51], v[2:3] op_sel_hi:[0,1,1]
	s_waitcnt vmcnt(12)
	v_pk_fma_f32 v[2:3], v[176:177], v[32:33], v[2:3] op_sel_hi:[0,1,1]
	s_waitcnt vmcnt(11)
	v_pk_fma_f32 v[2:3], v[178:179], v[52:53], v[2:3] op_sel_hi:[0,1,1]
	s_waitcnt vmcnt(10)
	v_pk_fma_f32 v[2:3], v[180:181], v[38:39], v[2:3] op_sel_hi:[0,1,1]
	s_waitcnt vmcnt(9)
	v_pk_fma_f32 v[2:3], v[182:183], v[46:47], v[2:3] op_sel_hi:[0,1,1]
	s_waitcnt vmcnt(8)
	v_pk_fma_f32 v[2:3], v[184:185], v[40:41], v[2:3] op_sel_hi:[0,1,1]
	s_waitcnt vmcnt(7)
	v_pk_fma_f32 v[2:3], v[136:137], v[48:49], v[2:3] op_sel_hi:[0,1,1]
	s_waitcnt vmcnt(6)
	v_pk_fma_f32 v[2:3], v[188:189], v[42:43], v[2:3] op_sel_hi:[0,1,1]
	s_waitcnt vmcnt(5)
	v_pk_fma_f32 v[2:3], v[138:139], v[130:131], v[2:3] op_sel_hi:[0,1,1]
	s_waitcnt vmcnt(4)
	v_pk_fma_f32 v[2:3], v[186:187], v[44:45], v[2:3] op_sel_hi:[0,1,1]
	s_waitcnt vmcnt(3)
	v_pk_fma_f32 v[2:3], v[96:97], v[132:133], v[2:3] op_sel_hi:[0,1,1]
	s_waitcnt vmcnt(2)
	v_pk_fma_f32 v[2:3], v[18:19], v[126:127], v[2:3] op_sel_hi:[0,1,1]
	s_waitcnt vmcnt(1)
	v_pk_fma_f32 v[2:3], v[140:141], v[134:135], v[2:3] op_sel_hi:[0,1,1]
	s_waitcnt vmcnt(0)
	v_pk_fma_f32 v[96:97], v[98:99], v[128:129], v[2:3] op_sel_hi:[0,1,1]
	s_cbranch_scc0 .LBB0_35
	global_load_dword v2, v[60:61], off offset:256 nt
	s_mov_b64 s[36:37], 0
	v_mov_b32_e32 v54, v116
	s_waitcnt vmcnt(0)
	v_mul_f32_e32 v3, v97, v2
	v_mul_f32_e32 v2, v96, v2
	v_mul_f32_e32 v4, 0.15915494, v3
	v_mul_f32_e32 v5, 0.15915494, v2
	v_rndne_f32_e32 v4, v4
	v_rndne_f32_e32 v5, v5
	v_fmac_f32_e32 v3, 0xc0c90fdb, v4
	v_fmac_f32_e32 v2, 0xc0c90fdb, v5
	v_fmac_f32_e32 v3, 0x343bbd2e, v4
	v_fmac_f32_e32 v2, 0x343bbd2e, v5
	v_mul_f32_e32 v3, 0.15915494, v3
	v_mul_f32_e32 v2, 0.15915494, v2
	v_sin_f32_e32 v3, v3
	v_sin_f32_e32 v2, v2
	ds_write_b32 v105, v3 offset:8192
	ds_write_b32 v106, v2 offset:10240
	s_waitcnt lgkmcnt(0)
	s_barrier
	global_load_dword v96, v[64:65], off nt
	s_waitcnt vmcnt(0)
	v_mov_b32_e32 v97, v96
.LBB0_37:
	v_lshl_add_u64 v[98:99], v[78:79], 0, s[36:37]
	ds_read_b128 v[14:17], v54
	ds_read_b128 v[10:13], v54 offset:16
	ds_read_b128 v[6:9], v54 offset:32
	ds_read_b128 v[2:5], v54 offset:48
	ds_read_b128 v[18:21], v54 offset:2048
	ds_read_b128 v[22:25], v54 offset:2064
	ds_read_b128 v[26:29], v54 offset:2080
	ds_read_b128 v[34:37], v54 offset:2096
	ds_read_b128 v[30:33], v54 offset:64
	ds_read_b128 v[38:41], v54 offset:80
	ds_read_b128 v[50:53], v54 offset:2112
	ds_read_b128 v[46:49], v54 offset:2128
	ds_read_b128 v[42:45], v54 offset:96
	ds_read_b128 v[126:129], v54 offset:112
	ds_read_b128 v[130:133], v54 offset:2144
	ds_read_b128 v[134:137], v54 offset:2160
	global_load_dword v138, v[98:99], off nt
	global_load_dword v140, v[98:99], off offset:256 nt
	global_load_dword v142, v[98:99], off offset:512 nt
	global_load_dword v144, v[98:99], off offset:768 nt
	global_load_dword v146, v[98:99], off offset:1024 nt
	global_load_dword v148, v[98:99], off offset:1280 nt
	global_load_dword v150, v[98:99], off offset:1536 nt
	global_load_dword v152, v[98:99], off offset:1792 nt
	global_load_dword v154, v[98:99], off offset:2048 nt
	global_load_dword v156, v[98:99], off offset:2304 nt
	global_load_dword v158, v[98:99], off offset:2560 nt
	global_load_dword v160, v[98:99], off offset:2816 nt
	global_load_dword v162, v[98:99], off offset:3072 nt
	global_load_dword v164, v[98:99], off offset:3328 nt
	global_load_dword v166, v[98:99], off offset:3584 nt
	global_load_dword v168, v[98:99], off offset:3840 nt
	v_add_co_u32_e32 v98, vcc, s56, v98
	s_waitcnt lgkmcnt(11)
	v_mov_b32_e32 v200, v18
	v_addc_co_u32_e32 v99, vcc, 0, v99, vcc
	global_load_dword v170, v[98:99], off nt
	global_load_dword v172, v[98:99], off offset:256 nt
	global_load_dword v174, v[98:99], off offset:512 nt
	global_load_dword v176, v[98:99], off offset:768 nt
	global_load_dword v178, v[98:99], off offset:1024 nt
	global_load_dword v180, v[98:99], off offset:1280 nt
	global_load_dword v182, v[98:99], off offset:1536 nt
	global_load_dword v184, v[98:99], off offset:1792 nt
	global_load_dword v186, v[98:99], off offset:2048 nt
	global_load_dword v188, v[98:99], off offset:2304 nt
	global_load_dword v190, v[98:99], off offset:2560 nt
	global_load_dword v192, v[98:99], off offset:2816 nt
	global_load_dword v194, v[98:99], off offset:3072 nt
	global_load_dword v196, v[98:99], off offset:3328 nt
	global_load_dword v198, v[98:99], off offset:3584 nt
	s_nop 0
	global_load_dword v98, v[98:99], off offset:3840 nt
	v_mov_b32_e32 v201, v14
	v_mov_b32_e32 v14, v19
	v_mov_b32_e32 v18, v20
	v_mov_b32_e32 v19, v16
	v_mov_b32_e32 v16, v21
	s_waitcnt lgkmcnt(10)
	v_mov_b32_e32 v20, v22
	v_mov_b32_e32 v21, v10
	v_mov_b32_e32 v10, v23
	v_mov_b32_e32 v22, v24
	v_mov_b32_e32 v23, v12
	v_mov_b32_e32 v12, v25
	s_waitcnt lgkmcnt(9)
	v_mov_b32_e32 v24, v26
	v_mov_b32_e32 v25, v6
	v_mov_b32_e32 v6, v27
	v_mov_b32_e32 v26, v28
	v_mov_b32_e32 v27, v8
	v_mov_b32_e32 v8, v29
	s_waitcnt lgkmcnt(8)
	v_mov_b32_e32 v28, v34
	v_mov_b32_e32 v29, v2
	v_mov_b32_e32 v2, v35
	v_mov_b32_e32 v34, v36
	v_mov_b32_e32 v35, v4
	v_mov_b32_e32 v4, v37
	s_waitcnt lgkmcnt(5)
	v_mov_b32_e32 v36, v50
	v_mov_b32_e32 v37, v30
	v_mov_b32_e32 v30, v51
	v_mov_b32_e32 v50, v52
	v_mov_b32_e32 v51, v32
	v_mov_b32_e32 v32, v53
	s_waitcnt lgkmcnt(4)
	v_mov_b32_e32 v52, v46
	v_mov_b32_e32 v53, v38
	v_mov_b32_e32 v38, v47
	v_mov_b32_e32 v46, v48
	v_mov_b32_e32 v47, v40
	v_mov_b32_e32 v40, v49
	s_waitcnt lgkmcnt(1)
	v_mov_b32_e32 v48, v130
	v_mov_b32_e32 v49, v42
	v_mov_b32_e32 v42, v131
	v_mov_b32_e32 v130, v132
	v_mov_b32_e32 v131, v44
	v_mov_b32_e32 v44, v133
	s_waitcnt lgkmcnt(0)
	v_mov_b32_e32 v132, v134
	v_mov_b32_e32 v133, v126
	v_mov_b32_e32 v126, v135
	s_add_u32 s36, s36, 0x2000
	v_mov_b32_e32 v134, v136
	v_mov_b32_e32 v135, v128
	s_addc_u32 s37, s37, 0
	v_mov_b32_e32 v128, v137
	v_add_u32_e32 v54, 0x80, v54
	s_cmpk_eq_i32 s36, 0x4000
	s_waitcnt vmcnt(31)
	v_pk_fma_f32 v[96:97], v[138:139], v[200:201], v[96:97] op_sel_hi:[0,1,1]
	s_waitcnt vmcnt(30)
	v_pk_fma_f32 v[14:15], v[140:141], v[14:15], v[96:97] op_sel_hi:[0,1,1]
	s_waitcnt vmcnt(29)
	v_pk_fma_f32 v[14:15], v[142:143], v[18:19], v[14:15] op_sel_hi:[0,1,1]
	s_waitcnt vmcnt(28)
	v_pk_fma_f32 v[14:15], v[144:145], v[16:17], v[14:15] op_sel_hi:[0,1,1]
	s_waitcnt vmcnt(27)
	v_pk_fma_f32 v[14:15], v[146:147], v[20:21], v[14:15] op_sel_hi:[0,1,1]
	s_waitcnt vmcnt(26)
	v_pk_fma_f32 v[10:11], v[148:149], v[10:11], v[14:15] op_sel_hi:[0,1,1]
	s_waitcnt vmcnt(25)
	v_pk_fma_f32 v[10:11], v[150:151], v[22:23], v[10:11] op_sel_hi:[0,1,1]
	s_waitcnt vmcnt(24)
	v_pk_fma_f32 v[10:11], v[152:153], v[12:13], v[10:11] op_sel_hi:[0,1,1]
	s_waitcnt vmcnt(23)
	v_pk_fma_f32 v[10:11], v[154:155], v[24:25], v[10:11] op_sel_hi:[0,1,1]
	s_waitcnt vmcnt(22)
	v_pk_fma_f32 v[6:7], v[156:157], v[6:7], v[10:11] op_sel_hi:[0,1,1]
	s_waitcnt vmcnt(21)
	v_pk_fma_f32 v[6:7], v[158:159], v[26:27], v[6:7] op_sel_hi:[0,1,1]
	s_waitcnt vmcnt(20)
	v_pk_fma_f32 v[6:7], v[160:161], v[8:9], v[6:7] op_sel_hi:[0,1,1]
	s_waitcnt vmcnt(19)
	v_pk_fma_f32 v[6:7], v[162:163], v[28:29], v[6:7] op_sel_hi:[0,1,1]
	s_waitcnt vmcnt(18)
	v_pk_fma_f32 v[2:3], v[164:165], v[2:3], v[6:7] op_sel_hi:[0,1,1]
	s_waitcnt vmcnt(17)
	v_pk_fma_f32 v[2:3], v[166:167], v[34:35], v[2:3] op_sel_hi:[0,1,1]
	s_waitcnt vmcnt(16)
	v_pk_fma_f32 v[2:3], v[168:169], v[4:5], v[2:3] op_sel_hi:[0,1,1]
	s_waitcnt vmcnt(15)
	v_pk_fma_f32 v[2:3], v[170:171], v[36:37], v[2:3] op_sel_hi:[0,1,1]
	s_waitcnt vmcnt(14)
	v_pk_fma_f32 v[2:3], v[172:173], v[30:31], v[2:3] op_sel_hi:[0,1,1]
	s_waitcnt vmcnt(13)
	v_pk_fma_f32 v[2:3], v[174:175], v[50:51], v[2:3] op_sel_hi:[0,1,1]
	s_waitcnt vmcnt(12)
	v_pk_fma_f32 v[2:3], v[176:177], v[32:33], v[2:3] op_sel_hi:[0,1,1]
	s_waitcnt vmcnt(11)
	v_pk_fma_f32 v[2:3], v[178:179], v[52:53], v[2:3] op_sel_hi:[0,1,1]
	s_waitcnt vmcnt(10)
	v_pk_fma_f32 v[2:3], v[180:181], v[38:39], v[2:3] op_sel_hi:[0,1,1]
	s_waitcnt vmcnt(9)
	v_pk_fma_f32 v[2:3], v[182:183], v[46:47], v[2:3] op_sel_hi:[0,1,1]
	s_waitcnt vmcnt(8)
	v_pk_fma_f32 v[2:3], v[184:185], v[40:41], v[2:3] op_sel_hi:[0,1,1]
	s_waitcnt vmcnt(7)
	v_pk_fma_f32 v[2:3], v[186:187], v[48:49], v[2:3] op_sel_hi:[0,1,1]
	s_waitcnt vmcnt(6)
	v_pk_fma_f32 v[2:3], v[188:189], v[42:43], v[2:3] op_sel_hi:[0,1,1]
	s_waitcnt vmcnt(5)
	v_pk_fma_f32 v[2:3], v[190:191], v[130:131], v[2:3] op_sel_hi:[0,1,1]
	s_waitcnt vmcnt(4)
	v_pk_fma_f32 v[2:3], v[192:193], v[44:45], v[2:3] op_sel_hi:[0,1,1]
	s_waitcnt vmcnt(3)
	v_pk_fma_f32 v[2:3], v[194:195], v[132:133], v[2:3] op_sel_hi:[0,1,1]
	s_waitcnt vmcnt(2)
	v_pk_fma_f32 v[2:3], v[196:197], v[126:127], v[2:3] op_sel_hi:[0,1,1]
	s_waitcnt vmcnt(1)
	v_pk_fma_f32 v[2:3], v[198:199], v[134:135], v[2:3] op_sel_hi:[0,1,1]
	s_waitcnt vmcnt(0)
	v_pk_fma_f32 v[96:97], v[98:99], v[128:129], v[2:3] op_sel_hi:[0,1,1]
	s_cbranch_scc0 .LBB0_37
	global_load_dword v10, v[60:61], off offset:512 nt
	v_mov_b32_e32 v6, s3
	v_mov_b32_e32 v7, s74
	v_mov_b32_e32 v8, s33
	v_mov_b32_e32 v9, s57
	v_mov_b32_e32 v95, v55
	v_mov_b32_e32 v93, v55
	v_cndmask_b32_e64 v3, v6, v7, s[16:17]
	v_cndmask_b32_e64 v2, v8, v9, s[16:17]
	v_lshlrev_b64 v[4:5], 7, v[94:95]
	v_cndmask_b32_e64 v7, v6, v7, s[14:15]
	v_cndmask_b32_e64 v6, v8, v9, s[14:15]
	v_lshlrev_b64 v[8:9], 7, v[92:93]
	v_mov_b32_e32 v89, v55
	v_lshl_add_u64 v[2:3], v[2:3], 0, v[4:5]
	v_lshl_add_u64 v[4:5], v[6:7], 0, v[8:9]
	v_cndmask_b32_e64 v54, v122, v123, s[16:17]
	v_lshl_add_u64 v[8:9], v[4:5], 0, v[88:89]
	v_lshl_add_u64 v[6:7], v[2:3], 0, v[54:55]
	v_cndmask_b32_e64 v54, v122, v123, s[14:15]
	v_lshl_add_u64 v[4:5], v[4:5], 0, v[54:55]
	v_lshl_add_u64 v[4:5], v[4:5], 0, v[88:89]
	v_lshl_add_u64 v[2:3], v[2:3], 0, v[88:89]
	v_lshl_add_u64 v[6:7], v[6:7], 0, v[88:89]
	s_mov_b64 s[14:15], -1
	s_waitcnt vmcnt(0)
	v_mul_f32_e32 v11, v97, v10
	v_mul_f32_e32 v10, v96, v10
	v_mul_f32_e32 v12, 0.15915494, v11
	v_mul_f32_e32 v13, 0.15915494, v10
	v_rndne_f32_e32 v12, v12
	v_rndne_f32_e32 v13, v13
	v_fmac_f32_e32 v11, 0xc0c90fdb, v12
	v_fmac_f32_e32 v10, 0xc0c90fdb, v13
	v_fmac_f32_e32 v11, 0x343bbd2e, v12
	v_fmac_f32_e32 v10, 0x343bbd2e, v13
	v_mul_f32_e32 v11, 0.15915494, v11
	v_mul_f32_e32 v10, 0.15915494, v10
	v_sin_f32_e32 v11, v11
	v_sin_f32_e32 v10, v10
	v_cvt_pk_bf16_f32 v12, v11, s0
	v_cvt_pk_bf16_f32 v13, v10, s0
	global_store_short v[8:9], v12, off
	v_lshlrev_b32_e32 v8, 16, v12
	v_lshlrev_b32_e32 v9, 16, v13
	v_sub_f32_e32 v8, v11, v8
	v_sub_f32_e32 v9, v10, v9
	v_cvt_pk_bf16_f32 v8, v8, s0
	v_cvt_pk_bf16_f32 v9, v9, s0
	global_store_short v[4:5], v8, off
	global_store_short v[2:3], v13, off
	global_store_short v[6:7], v9, off
	s_barrier
	s_branch .LBB0_45

.LBB0_43:
	v_add_co_u32_e32 v8, vcc, 0x2000, v4
	global_load_dword v7, v[4:5], off nt
	s_nop 0
	v_addc_co_u32_e32 v9, vcc, 0, v5, vcc
	global_load_dword v8, v[8:9], off nt
	s_mov_b32 s36, 0x3fb8aa3b
	v_add_u32_e32 v6, 0x200, v6
	s_movk_i32 s30, 0x5ff
	s_mov_b32 s37, 0xc2ce8ed0
	v_cmp_lt_u32_e32 vcc, s30, v6
	s_mov_b32 s38, 0x42b17218
	s_or_b64 s[16:17], vcc, s[16:17]
	v_lshl_add_u64 v[4:5], v[4:5], 0, s[34:35]
	s_waitcnt vmcnt(0)
	v_sub_f32_e32 v7, v8, v7
	v_mul_f32_e32 v8, 0x3fb8aa3b, v7
	v_fma_f32 v9, v7, s36, -v8
	v_rndne_f32_e32 v10, v8
	v_fmac_f32_e32 v9, 0x32a5705f, v7
	v_sub_f32_e32 v8, v8, v10
	v_add_f32_e32 v8, v8, v9
	v_cvt_i32_f32_e32 v10, v10
	v_exp_f32_e32 v8, v8
	v_cmp_ngt_f32_e32 vcc, s37, v7
	v_ldexp_f32 v8, v8, v10
	s_nop 0
	v_cndmask_b32_e32 v8, 0, v8, vcc
	v_cmp_nlt_f32_e32 vcc, s38, v7
	s_nop 1
	v_cndmask_b32_e32 v7, v124, v8, vcc
	v_add_f32_e32 v7, 1.0, v7
	v_div_scale_f32 v8, s[36:37], v7, v7, 1.0
	v_rcp_f32_e32 v9, v8
	v_div_scale_f32 v10, vcc, 1.0, v7, 1.0
	v_fma_f32 v11, -v8, v9, 1.0
	v_fmac_f32_e32 v9, v11, v9
	v_mul_f32_e32 v11, v10, v9
	v_fma_f32 v12, -v8, v11, v10
	v_fmac_f32_e32 v11, v12, v9
	v_fma_f32 v8, -v8, v11, v10
	v_div_fmas_f32 v8, v8, v9, v11
	v_div_fixup_f32 v7, v8, v7, 1.0
	global_store_dword v[2:3], v7, off
	v_lshl_add_u64 v[2:3], v[2:3], 0, s[34:35]
	s_andn2_b64 exec, exec, s[16:17]
	s_cbranch_execnz .LBB0_43
	s_or_b64 exec, exec, s[16:17]

.LBB0_47:
	s_movk_i32 s16, 0x400
	v_cmp_gt_u32_e32 vcc, s16, v7
	s_movk_i32 s16, 0x9ff
	s_nop 0
	v_cndmask_b32_e32 v9, v5, v3, vcc
	v_cndmask_b32_e32 v8, v4, v2, vcc
	global_load_dword v8, v[8:9], off nt
	v_add_u32_e32 v9, 0x200, v7
	v_cmp_lt_u32_e32 vcc, s16, v7
	v_lshl_add_u64 v[4:5], v[4:5], 0, s[34:35]
	v_lshl_add_u64 v[2:3], v[2:3], 0, s[34:35]
	s_or_b64 s[14:15], vcc, s[14:15]
	s_waitcnt vmcnt(0)
	v_mul_f32_e32 v7, 0xbfb8aa3b, v8
	v_exp_f32_e32 v10, v7
	v_mov_b32_e32 v7, v9
	v_add_f32_e32 v9, 1.0, v10
	v_rcp_f32_e32 v9, v9
	s_nop 0
	v_mul_f32_e32 v8, v8, v9
	ds_write_b32 v6, v8
	v_add_u32_e32 v6, 0x800, v6
	s_andn2_b64 exec, exec, s[14:15]
	s_cbranch_execnz .LBB0_47
	s_or_b64 exec, exec, s[14:15]
	s_lshl_b32 s14, s90, 5
	s_add_i32 s30, s14, 0xffff9800
	v_lshl_add_u64 v[2:3], s[30:31], 2, v[90:91]
	v_add_co_u32_e32 v4, vcc, 0x6000, v2
	s_waitcnt lgkmcnt(0)
	s_nop 0
	v_addc_co_u32_e32 v5, vcc, 0, v3, vcc
	v_add_co_u32_e32 v6, vcc, 0xc000, v2
	s_barrier
	s_nop 0
	v_addc_co_u32_e32 v7, vcc, 0, v3, vcc
	global_load_dword v38, v[2:3], off nt
	global_load_dword v39, v[4:5], off nt
	global_load_dword v40, v[6:7], off nt
	v_add_co_u32_e32 v4, vcc, 0x12000, v2
	s_mov_b32 s14, 0x60000
	s_nop 0
	v_addc_co_u32_e32 v5, vcc, 0, v3, vcc
	v_add_co_u32_e32 v6, vcc, 0x18000, v2
	s_nop 1
	v_addc_co_u32_e32 v7, vcc, 0, v3, vcc
	v_add_co_u32_e32 v8, vcc, 0x1e000, v2
	s_nop 1
	v_addc_co_u32_e32 v9, vcc, 0, v3, vcc
	v_add_co_u32_e32 v10, vcc, 0x24000, v2
	s_nop 1
	v_addc_co_u32_e32 v11, vcc, 0, v3, vcc
	v_add_co_u32_e32 v12, vcc, 0x2a000, v2
	s_nop 1
	v_addc_co_u32_e32 v13, vcc, 0, v3, vcc
	global_load_dword v41, v[4:5], off nt
	global_load_dword v42, v[6:7], off nt
	global_load_dword v43, v[8:9], off nt
	global_load_dword v44, v[10:11], off nt
	global_load_dword v45, v[12:13], off nt
	v_add_co_u32_e32 v4, vcc, 0x30000, v2
	s_nop 1
	v_addc_co_u32_e32 v5, vcc, 0, v3, vcc
	global_load_dword v46, v[4:5], off nt
	v_add_co_u32_e32 v4, vcc, 0x36000, v2
	s_nop 1
	v_addc_co_u32_e32 v5, vcc, 0, v3, vcc
	v_add_co_u32_e32 v6, vcc, 0x3c000, v2
	s_nop 1
	v_addc_co_u32_e32 v7, vcc, 0, v3, vcc
	global_load_dword v47, v[4:5], off nt
	global_load_dword v48, v[6:7], off nt
	v_add_co_u32_e32 v4, vcc, 0x42000, v2
	s_nop 1
	v_addc_co_u32_e32 v5, vcc, 0, v3, vcc
	global_load_dword v49, v[4:5], off nt
	v_add_co_u32_e32 v4, vcc, 0x48000, v2
	s_nop 1
	v_addc_co_u32_e32 v5, vcc, 0, v3, vcc
	v_add_co_u32_e32 v6, vcc, 0x4e000, v2
	s_nop 1
	v_addc_co_u32_e32 v7, vcc, 0, v3, vcc
	v_add_co_u32_e32 v8, vcc, 0x54000, v2
	s_nop 1
	v_addc_co_u32_e32 v9, vcc, 0, v3, vcc
	v_add_co_u32_e32 v10, vcc, 0x5a000, v2
	s_nop 1
	v_addc_co_u32_e32 v11, vcc, 0, v3, vcc
	global_load_dword v50, v[4:5], off nt
	global_load_dword v51, v[6:7], off nt
	global_load_dword v52, v[8:9], off nt
	global_load_dword v53, v[10:11], off nt
	ds_read_b128 v[6:9], v108
	ds_read_b128 v[10:13], v108 offset:16
	ds_read_b128 v[14:17], v108 offset:4096
	ds_read_b128 v[18:21], v108 offset:32
	ds_read_b128 v[22:25], v108 offset:48
	ds_read_b128 v[26:29], v108 offset:8192
	ds_read_b128 v[30:33], v108 offset:4112
	ds_read_b128 v[34:37], v108 offset:8208
	s_waitcnt vmcnt(15) lgkmcnt(7)
	v_fma_f32 v4, v38, v6, 0
	s_waitcnt vmcnt(14)
	v_fmac_f32_e32 v4, v39, v7
	s_waitcnt lgkmcnt(5)
	v_fma_f32 v5, v38, v14, 0
	s_waitcnt vmcnt(13)
	v_fmac_f32_e32 v4, v40, v8
	v_fmac_f32_e32 v5, v39, v15
	s_waitcnt lgkmcnt(2)
	v_fma_f32 v6, v38, v26, 0
	v_fmac_f32_e32 v5, v40, v16
	v_fmac_f32_e32 v6, v39, v27
	v_fmac_f32_e32 v6, v40, v28
	s_waitcnt vmcnt(12)
	v_fmac_f32_e32 v4, v41, v9
	s_waitcnt vmcnt(11)
	v_fmac_f32_e32 v4, v42, v10
	v_fmac_f32_e32 v5, v41, v17
	s_waitcnt vmcnt(10)
	v_fmac_f32_e32 v4, v43, v11
	ds_read_b128 v[8:11], v108 offset:4128
	s_waitcnt lgkmcnt(2)
	v_fmac_f32_e32 v5, v42, v30
	s_waitcnt vmcnt(9)
	v_fmac_f32_e32 v4, v44, v12
	v_fmac_f32_e32 v6, v41, v29
	v_fmac_f32_e32 v5, v43, v31
	s_waitcnt vmcnt(8)
	v_fmac_f32_e32 v4, v45, v13
	ds_read_b128 v[12:15], v108 offset:8224
	v_fmac_f32_e32 v5, v44, v32
	ds_read_b128 v[26:29], v108 offset:4144
	s_waitcnt lgkmcnt(3)
	v_fmac_f32_e32 v6, v42, v34
	v_fmac_f32_e32 v6, v43, v35
	v_fmac_f32_e32 v5, v45, v33
	v_fmac_f32_e32 v6, v44, v36
	s_waitcnt vmcnt(7) lgkmcnt(2)
	v_fmac_f32_e32 v5, v46, v8
	v_add_co_u32_e32 v8, vcc, s14, v2
	v_fmac_f32_e32 v6, v45, v37
	s_waitcnt vmcnt(6)
	v_fmac_f32_e32 v5, v47, v9
	v_addc_co_u32_e32 v9, vcc, 0, v3, vcc
	s_mov_b32 s14, 0x66000
	ds_read_b128 v[30:33], v108 offset:8240
	s_waitcnt lgkmcnt(2)
	v_fmac_f32_e32 v6, v46, v12
	v_add_co_u32_e32 v12, vcc, s14, v2
	v_fmac_f32_e32 v6, v47, v13
	s_nop 0
	v_addc_co_u32_e32 v13, vcc, 0, v3, vcc
	s_mov_b32 s14, 0x6c000
	global_load_dword v7, v[8:9], off nt
	global_load_dword v36, v[12:13], off nt
	v_add_co_u32_e32 v8, vcc, s14, v2
	s_mov_b32 s14, 0x72000
	s_nop 0
	v_addc_co_u32_e32 v9, vcc, 0, v3, vcc
	v_add_co_u32_e32 v12, vcc, s14, v2
	s_mov_b32 s14, 0x78000
	s_nop 0
	v_addc_co_u32_e32 v13, vcc, 0, v3, vcc
	v_add_co_u32_e32 v16, vcc, s14, v2
	s_mov_b32 s14, 0x7e000
	s_nop 0
	v_addc_co_u32_e32 v17, vcc, 0, v3, vcc
	v_fmac_f32_e32 v4, v46, v18
	v_add_co_u32_e32 v18, vcc, s14, v2
	v_fmac_f32_e32 v4, v47, v19
	s_nop 0
	v_addc_co_u32_e32 v19, vcc, 0, v3, vcc
	s_mov_b32 s14, 0x84000
	s_waitcnt vmcnt(7)
	v_fmac_f32_e32 v4, v48, v20
	v_add_co_u32_e32 v20, vcc, s14, v2
	s_waitcnt vmcnt(6)
	v_fmac_f32_e32 v4, v49, v21
	v_addc_co_u32_e32 v21, vcc, 0, v3, vcc
	s_mov_b32 s14, 0x8a000
	v_add_co_u32_e32 v34, vcc, s14, v2
	s_mov_b32 s14, 0x90000
	s_nop 0
	v_addc_co_u32_e32 v35, vcc, 0, v3, vcc
	global_load_dword v37, v[8:9], off nt
	global_load_dword v38, v[12:13], off nt
	global_load_dword v39, v[16:17], off nt
	global_load_dword v40, v[18:19], off nt
	global_load_dword v41, v[20:21], off nt
	s_nop 0
	global_load_dword v34, v[34:35], off nt
	v_add_co_u32_e32 v8, vcc, s14, v2
	s_mov_b32 s14, 0x96000
	s_nop 0
	v_addc_co_u32_e32 v9, vcc, 0, v3, vcc
	global_load_dword v35, v[8:9], off nt
	v_add_co_u32_e32 v8, vcc, s14, v2
	s_mov_b32 s14, 0x9c000
	s_nop 0
	v_addc_co_u32_e32 v9, vcc, 0, v3, vcc
	v_add_co_u32_e32 v12, vcc, s14, v2
	s_mov_b32 s14, 0xa2000
	s_nop 0
	v_addc_co_u32_e32 v13, vcc, 0, v3, vcc
	v_add_co_u32_e32 v16, vcc, s14, v2
	s_mov_b32 s14, 0xa8000
	s_nop 0
	v_addc_co_u32_e32 v17, vcc, 0, v3, vcc
	global_load_dword v42, v[8:9], off nt
	global_load_dword v43, v[12:13], off nt
	global_load_dword v44, v[16:17], off nt
	v_add_co_u32_e32 v12, vcc, s14, v2
	s_mov_b32 s14, 0xae000
	s_nop 0
	v_addc_co_u32_e32 v13, vcc, 0, v3, vcc
	v_fmac_f32_e32 v6, v48, v14
	v_add_co_u32_e32 v14, vcc, s14, v2
	v_fmac_f32_e32 v5, v48, v10
	v_fmac_f32_e32 v6, v49, v15
	v_addc_co_u32_e32 v15, vcc, 0, v3, vcc
	s_mov_b32 s14, 0xb4000
	v_fmac_f32_e32 v5, v49, v11
	v_add_co_u32_e32 v16, vcc, s14, v2
	ds_read_b128 v[8:11], v108 offset:64
	s_waitcnt vmcnt(15)
	v_fmac_f32_e32 v4, v50, v22
	s_waitcnt lgkmcnt(1)
	v_fmac_f32_e32 v6, v50, v30
	v_addc_co_u32_e32 v17, vcc, 0, v3, vcc
	s_mov_b32 s14, 0xba000
	s_waitcnt vmcnt(14)
	v_fmac_f32_e32 v4, v51, v23
	v_fmac_f32_e32 v6, v51, v31
	v_add_co_u32_e32 v18, vcc, s14, v2
	s_waitcnt vmcnt(13)
	v_fmac_f32_e32 v4, v52, v24
	v_fmac_f32_e32 v6, v52, v32
	v_addc_co_u32_e32 v19, vcc, 0, v3, vcc
	s_waitcnt vmcnt(12)
	v_fmac_f32_e32 v4, v53, v25
	v_fmac_f32_e32 v6, v53, v33
	global_load_dword v32, v[12:13], off nt
	global_load_dword v33, v[14:15], off nt
	global_load_dword v45, v[16:17], off nt
	global_load_dword v46, v[18:19], off nt
	ds_read_b128 v[12:15], v108 offset:4160
	ds_read_b128 v[16:19], v108 offset:8256
	ds_read_b128 v[20:23], v108 offset:80
	v_fmac_f32_e32 v5, v50, v26
	s_waitcnt vmcnt(15) lgkmcnt(3)
	v_fmac_f32_e32 v4, v7, v8
	v_fmac_f32_e32 v5, v51, v27
	s_waitcnt vmcnt(14)
	v_fmac_f32_e32 v4, v36, v9
	v_fmac_f32_e32 v5, v52, v28
	v_fmac_f32_e32 v5, v53, v29
	ds_read_b128 v[24:27], v108 offset:4176
	s_waitcnt lgkmcnt(3)
	v_fmac_f32_e32 v5, v7, v12
	v_fmac_f32_e32 v5, v36, v13
	s_waitcnt lgkmcnt(2)
	v_fmac_f32_e32 v6, v7, v16
	ds_read_b128 v[28:31], v108 offset:8272
	v_fmac_f32_e32 v6, v36, v17
	s_mov_b32 s14, 0xc0000
	s_waitcnt vmcnt(13)
	v_fmac_f32_e32 v4, v37, v10
	s_waitcnt vmcnt(12)
	v_fmac_f32_e32 v4, v38, v11
	ds_read_b128 v[8:11], v108 offset:96
	s_waitcnt vmcnt(11) lgkmcnt(3)
	v_fmac_f32_e32 v4, v39, v20
	s_waitcnt vmcnt(10)
	v_fmac_f32_e32 v4, v40, v21
	v_fmac_f32_e32 v5, v37, v14
	s_waitcnt vmcnt(9)
	v_fmac_f32_e32 v4, v41, v22
	v_fmac_f32_e32 v5, v38, v15
	s_waitcnt vmcnt(8)
	v_fmac_f32_e32 v4, v34, v23
	v_fmac_f32_e32 v6, v37, v18
	s_waitcnt lgkmcnt(2)
	v_fmac_f32_e32 v5, v39, v24
	s_waitcnt vmcnt(7) lgkmcnt(0)
	v_fmac_f32_e32 v4, v35, v8
	v_add_co_u32_e32 v8, vcc, s14, v2
	v_fmac_f32_e32 v6, v38, v19
	v_fmac_f32_e32 v5, v40, v25
	ds_read_b128 v[12:15], v108 offset:4192
	ds_read_b128 v[16:19], v108 offset:8288
	ds_read_b128 v[20:23], v108 offset:112
	s_mov_b32 s14, 0xc6000
	v_fmac_f32_e32 v5, v41, v26
	v_fmac_f32_e32 v5, v34, v27
	v_fmac_f32_e32 v6, v39, v28
	s_waitcnt lgkmcnt(2)
	v_fmac_f32_e32 v5, v35, v12
	v_fmac_f32_e32 v6, v40, v29
	v_fmac_f32_e32 v6, v41, v30
	v_fmac_f32_e32 v6, v34, v31
	s_waitcnt vmcnt(6)
	v_fmac_f32_e32 v4, v42, v9
	v_addc_co_u32_e32 v9, vcc, 0, v3, vcc
	s_waitcnt vmcnt(5)
	v_fmac_f32_e32 v4, v43, v10
	v_add_co_u32_e32 v10, vcc, s14, v2
	s_waitcnt vmcnt(4)
	v_fmac_f32_e32 v4, v44, v11
	v_addc_co_u32_e32 v11, vcc, 0, v3, vcc
	s_mov_b32 s14, 0xcc000
	v_add_co_u32_e32 v12, vcc, s14, v2
	v_fmac_f32_e32 v5, v42, v13
	s_nop 0
	v_addc_co_u32_e32 v13, vcc, 0, v3, vcc
	s_mov_b32 s14, 0xd2000
	v_fmac_f32_e32 v5, v43, v14
	v_add_co_u32_e32 v14, vcc, s14, v2
	v_fmac_f32_e32 v5, v44, v15
	s_nop 0
	v_addc_co_u32_e32 v15, vcc, 0, v3, vcc
	s_mov_b32 s14, 0xd8000
	s_waitcnt lgkmcnt(1)
	v_fmac_f32_e32 v6, v35, v16
	v_add_co_u32_e32 v16, vcc, s14, v2
	v_fmac_f32_e32 v6, v42, v17
	s_nop 0
	v_addc_co_u32_e32 v17, vcc, 0, v3, vcc
	s_mov_b32 s14, 0xde000
	ds_read_b128 v[24:27], v108 offset:4208
	ds_read_b128 v[28:31], v108 offset:8304
	global_load_dword v7, v[8:9], off nt
	global_load_dword v34, v[10:11], off nt
	global_load_dword v35, v[12:13], off nt
	global_load_dword v36, v[14:15], off nt
	global_load_dword v37, v[16:17], off nt
	v_add_co_u32_e32 v8, vcc, s14, v2
	s_mov_b32 s14, 0xe4000
	s_nop 0
	v_addc_co_u32_e32 v9, vcc, 0, v3, vcc
	v_add_co_u32_e32 v10, vcc, s14, v2
	s_mov_b32 s14, 0xea000
	s_nop 0
	v_addc_co_u32_e32 v11, vcc, 0, v3, vcc
	v_add_co_u32_e32 v12, vcc, s14, v2
	s_mov_b32 s14, 0xf0000
	s_nop 0
	v_addc_co_u32_e32 v13, vcc, 0, v3, vcc
	global_load_dword v38, v[8:9], off nt
	global_load_dword v39, v[10:11], off nt
	global_load_dword v40, v[12:13], off nt
	v_add_co_u32_e32 v8, vcc, s14, v2
	s_mov_b32 s14, 0xf6000
	s_nop 0
	v_addc_co_u32_e32 v9, vcc, 0, v3, vcc
	v_add_co_u32_e32 v12, vcc, s14, v2
	s_mov_b32 s14, 0xfc000
	s_nop 0
	v_addc_co_u32_e32 v13, vcc, 0, v3, vcc
	v_add_co_u32_e32 v14, vcc, s14, v2
	s_mov_b32 s14, 0x102000
	s_nop 0
	v_addc_co_u32_e32 v15, vcc, 0, v3, vcc
	v_add_co_u32_e32 v16, vcc, s14, v2
	s_mov_b32 s14, 0x108000
	s_nop 0
	v_addc_co_u32_e32 v17, vcc, 0, v3, vcc
	v_fmac_f32_e32 v6, v43, v18
	v_add_co_u32_e32 v18, vcc, s14, v2
	v_fmac_f32_e32 v6, v44, v19
	s_nop 0
	v_addc_co_u32_e32 v19, vcc, 0, v3, vcc
	s_waitcnt vmcnt(11) lgkmcnt(2)
	v_fmac_f32_e32 v4, v32, v20
	v_add_co_u32_e32 v20, vcc, s21, v2
	global_load_dword v44, v[8:9], off nt
	s_waitcnt vmcnt(11)
	v_fmac_f32_e32 v4, v33, v21
	v_addc_co_u32_e32 v21, vcc, 0, v3, vcc
	ds_read_b128 v[8:11], v108 offset:128
	s_waitcnt lgkmcnt(2)
	v_fmac_f32_e32 v5, v32, v24
	s_waitcnt lgkmcnt(1)
	v_fmac_f32_e32 v6, v32, v28
	s_waitcnt vmcnt(10)
	v_fmac_f32_e32 v4, v45, v22
	v_add_co_u32_e32 v22, vcc, s20, v2
	v_fmac_f32_e32 v5, v33, v25
	v_fmac_f32_e32 v6, v33, v29
	s_waitcnt vmcnt(9)
	v_fmac_f32_e32 v4, v46, v23
	v_addc_co_u32_e32 v23, vcc, 0, v3, vcc
	v_fmac_f32_e32 v5, v45, v26
	v_fmac_f32_e32 v6, v45, v30
	v_add_co_u32_e32 v24, vcc, s22, v2
	v_fmac_f32_e32 v5, v46, v27
	v_fmac_f32_e32 v6, v46, v31
	v_addc_co_u32_e32 v25, vcc, 0, v3, vcc
	global_load_dword v45, v[12:13], off nt
	global_load_dword v46, v[14:15], off nt
	global_load_dword v47, v[16:17], off nt
	global_load_dword v48, v[18:19], off nt
	global_load_dword v49, v[20:21], off nt
	global_load_dword v50, v[22:23], off nt
	global_load_dword v51, v[24:25], off nt
	ds_read_b128 v[12:15], v108 offset:4224
	ds_read_b128 v[16:19], v108 offset:8320
	ds_read_b128 v[20:23], v108 offset:144
	ds_read_b128 v[24:27], v108 offset:4240
	ds_read_b128 v[28:31], v108 offset:8336
	v_add_co_u32_e32 v32, vcc, s58, v2
	s_waitcnt vmcnt(15) lgkmcnt(5)
	v_fmac_f32_e32 v4, v7, v8
	s_waitcnt vmcnt(14)
	v_fmac_f32_e32 v4, v34, v9
	s_waitcnt vmcnt(13)
	v_fmac_f32_e32 v4, v35, v10
	s_waitcnt lgkmcnt(4)
	v_fmac_f32_e32 v5, v7, v12
	s_waitcnt lgkmcnt(3)
	v_fmac_f32_e32 v6, v7, v16
	s_waitcnt vmcnt(12)
	v_fmac_f32_e32 v4, v36, v11
	v_fmac_f32_e32 v5, v34, v13
	v_fmac_f32_e32 v6, v34, v17
	s_waitcnt vmcnt(11) lgkmcnt(2)
	v_fmac_f32_e32 v4, v37, v20
	v_fmac_f32_e32 v5, v35, v14
	v_fmac_f32_e32 v6, v35, v18
	v_fmac_f32_e32 v5, v36, v15
	v_fmac_f32_e32 v6, v36, v19
	ds_read_b128 v[12:15], v108 offset:4256
	s_waitcnt lgkmcnt(2)
	v_fmac_f32_e32 v5, v37, v24
	v_addc_co_u32_e32 v33, vcc, 0, v3, vcc
	v_add_co_u32_e32 v34, vcc, s59, v2
	s_waitcnt vmcnt(10)
	v_fmac_f32_e32 v4, v38, v21
	s_waitcnt vmcnt(9)
	v_fmac_f32_e32 v4, v39, v22
	s_waitcnt vmcnt(8)
	v_fmac_f32_e32 v4, v40, v23
	ds_read_b128 v[20:23], v108 offset:4272
	s_waitcnt lgkmcnt(2)
	v_fmac_f32_e32 v6, v37, v28
	v_fmac_f32_e32 v5, v38, v25
	v_fmac_f32_e32 v6, v38, v29
	v_fmac_f32_e32 v5, v39, v26
	v_fmac_f32_e32 v6, v39, v30
	v_addc_co_u32_e32 v35, vcc, 0, v3, vcc
	ds_read_b128 v[8:11], v108 offset:160
	ds_read_b128 v[16:19], v108 offset:176
	v_fmac_f32_e32 v5, v40, v27
	v_fmac_f32_e32 v6, v40, v31
	ds_read_b128 v[24:27], v108 offset:8352
	ds_read_b128 v[28:31], v108 offset:8368
	global_load_dword v7, v[32:33], off nt
	global_load_dword v52, v[34:35], off nt
	v_add_co_u32_e32 v32, vcc, s60, v2
	s_waitcnt vmcnt(9) lgkmcnt(3)
	v_fmac_f32_e32 v4, v44, v8
	v_addc_co_u32_e32 v33, vcc, 0, v3, vcc
	v_add_co_u32_e32 v34, vcc, s61, v2
	v_fmac_f32_e32 v5, v44, v12
	s_nop 0
	v_addc_co_u32_e32 v35, vcc, 0, v3, vcc
	v_add_co_u32_e32 v36, vcc, s62, v2
	s_waitcnt lgkmcnt(1)
	v_fmac_f32_e32 v6, v44, v24
	v_addc_co_u32_e32 v37, vcc, 0, v3, vcc
	v_add_co_u32_e32 v38, vcc, s63, v2
	s_waitcnt vmcnt(8)
	v_fmac_f32_e32 v4, v45, v9
	v_addc_co_u32_e32 v39, vcc, 0, v3, vcc
	v_add_co_u32_e32 v40, vcc, s75, v2
	v_fmac_f32_e32 v5, v45, v13
	s_nop 0
	v_addc_co_u32_e32 v41, vcc, 0, v3, vcc
	v_add_co_u32_e32 v42, vcc, s76, v2
	s_waitcnt vmcnt(7)
	v_fmac_f32_e32 v4, v46, v10
	v_addc_co_u32_e32 v43, vcc, 0, v3, vcc
	global_load_dword v53, v[32:33], off nt
	global_load_dword v54, v[34:35], off nt
	global_load_dword v89, v[36:37], off nt
	global_load_dword v92, v[38:39], off nt
	s_nop 0
	global_load_dword v40, v[40:41], off nt
	s_nop 0
	global_load_dword v41, v[42:43], off nt
	v_add_co_u32_e32 v32, vcc, s77, v2
	v_fmac_f32_e32 v5, v46, v14
	s_nop 0
	v_addc_co_u32_e32 v33, vcc, 0, v3, vcc
	global_load_dword v42, v[32:33], off nt
	v_add_co_u32_e32 v32, vcc, s78, v2
	s_waitcnt vmcnt(13)
	v_fmac_f32_e32 v4, v47, v11
	v_addc_co_u32_e32 v33, vcc, 0, v3, vcc
	v_add_co_u32_e32 v34, vcc, s79, v2
	v_fmac_f32_e32 v5, v47, v15
	s_nop 0
	v_addc_co_u32_e32 v35, vcc, 0, v3, vcc
	v_add_co_u32_e32 v36, vcc, s80, v2
	v_fmac_f32_e32 v6, v45, v25
	s_nop 0
	v_addc_co_u32_e32 v37, vcc, 0, v3, vcc
	v_add_co_u32_e32 v38, vcc, s81, v2
	s_waitcnt vmcnt(12)
	v_fmac_f32_e32 v4, v48, v16
	v_addc_co_u32_e32 v39, vcc, 0, v3, vcc
	global_load_dword v43, v[32:33], off nt
	global_load_dword v93, v[34:35], off nt
	s_nop 0
	global_load_dword v36, v[36:37], off nt
	s_nop 0
	global_load_dword v37, v[38:39], off nt
	v_add_co_u32_e32 v32, vcc, s82, v2
	v_fmac_f32_e32 v5, v48, v20
	s_nop 0
	v_addc_co_u32_e32 v33, vcc, 0, v3, vcc
	v_add_co_u32_e32 v34, vcc, s83, v2
	v_fmac_f32_e32 v6, v46, v26
	s_nop 0
	v_addc_co_u32_e32 v35, vcc, 0, v3, vcc
	v_add_co_u32_e32 v2, vcc, s84, v2
	global_load_dword v32, v[32:33], off nt
	s_nop 0
	global_load_dword v33, v[34:35], off nt
	v_addc_co_u32_e32 v3, vcc, 0, v3, vcc
	global_load_dword v2, v[2:3], off nt
	ds_read_b128 v[8:11], v108 offset:192
	s_waitcnt vmcnt(18)
	v_fmac_f32_e32 v4, v49, v17
	v_fmac_f32_e32 v5, v49, v21
	v_fmac_f32_e32 v6, v47, v27
	s_waitcnt vmcnt(17)
	v_fmac_f32_e32 v4, v50, v18
	v_fmac_f32_e32 v5, v50, v22
	s_waitcnt lgkmcnt(1)
	v_fmac_f32_e32 v6, v48, v28
	s_waitcnt vmcnt(16)
	v_fmac_f32_e32 v4, v51, v19
	v_fmac_f32_e32 v5, v51, v23
	ds_read_b128 v[12:15], v108 offset:4288
	ds_read_b128 v[16:19], v108 offset:8384
	ds_read_b128 v[20:23], v108 offset:208
	v_fmac_f32_e32 v6, v49, v29
	s_waitcnt vmcnt(15) lgkmcnt(3)
	v_fmac_f32_e32 v4, v7, v8
	v_fmac_f32_e32 v6, v50, v30
	s_waitcnt vmcnt(14)
	v_fmac_f32_e32 v4, v52, v9
	v_fmac_f32_e32 v6, v51, v31
	ds_read_b128 v[24:27], v108 offset:4304
	ds_read_b128 v[28:31], v108 offset:8400
	s_waitcnt lgkmcnt(4)
	v_fmac_f32_e32 v5, v7, v12
	s_waitcnt lgkmcnt(3)
	v_fmac_f32_e32 v6, v7, v16
	v_fmac_f32_e32 v5, v52, v13
	v_fmac_f32_e32 v6, v52, v17
	s_waitcnt vmcnt(13)
	v_fmac_f32_e32 v4, v53, v10
	s_waitcnt vmcnt(12)
	v_fmac_f32_e32 v4, v54, v11
	s_waitcnt vmcnt(11) lgkmcnt(2)
	v_fmac_f32_e32 v4, v89, v20
	v_fmac_f32_e32 v5, v53, v14
	v_fmac_f32_e32 v6, v53, v18
	s_waitcnt vmcnt(10)
	v_fmac_f32_e32 v4, v92, v21
	ds_read_b128 v[8:11], v108 offset:224
	v_fmac_f32_e32 v5, v54, v15
	v_fmac_f32_e32 v6, v54, v19
	s_waitcnt vmcnt(9)
	v_fmac_f32_e32 v4, v40, v22
	s_waitcnt lgkmcnt(2)
	v_fmac_f32_e32 v5, v89, v24
	s_waitcnt lgkmcnt(1)
	v_fmac_f32_e32 v6, v89, v28
	s_waitcnt vmcnt(8)
	v_fmac_f32_e32 v4, v41, v23
	ds_read_b128 v[12:15], v108 offset:4320
	ds_read_b128 v[16:19], v108 offset:8416
	ds_read_b128 v[20:23], v108 offset:240
	v_fmac_f32_e32 v5, v92, v25
	v_fmac_f32_e32 v6, v92, v29
	v_fmac_f32_e32 v5, v40, v26
	v_fmac_f32_e32 v6, v40, v30
	v_fmac_f32_e32 v5, v41, v27
	v_fmac_f32_e32 v6, v41, v31
	s_waitcnt vmcnt(7) lgkmcnt(3)
	v_fmac_f32_e32 v4, v42, v8
	ds_read_b128 v[24:27], v108 offset:4336
	ds_read_b128 v[28:31], v108 offset:8432
	s_waitcnt lgkmcnt(4)
	v_fmac_f32_e32 v5, v42, v12
	s_waitcnt lgkmcnt(3)
	v_fmac_f32_e32 v6, v42, v16
	s_waitcnt vmcnt(6)
	v_fmac_f32_e32 v4, v43, v9
	v_fmac_f32_e32 v5, v43, v13
	v_fmac_f32_e32 v6, v43, v17
	s_waitcnt vmcnt(5)
	v_fmac_f32_e32 v4, v93, v10
	v_fmac_f32_e32 v5, v93, v14
	v_fmac_f32_e32 v6, v93, v18
	s_waitcnt vmcnt(4)
	v_fmac_f32_e32 v4, v36, v11
	v_fmac_f32_e32 v5, v36, v15
	v_fmac_f32_e32 v6, v36, v19
	s_waitcnt vmcnt(3) lgkmcnt(2)
	v_fmac_f32_e32 v4, v37, v20
	s_waitcnt lgkmcnt(1)
	v_fmac_f32_e32 v5, v37, v24
	s_waitcnt lgkmcnt(0)
	v_fmac_f32_e32 v6, v37, v28
	s_waitcnt vmcnt(2)
	v_fmac_f32_e32 v4, v32, v21
	v_fmac_f32_e32 v5, v32, v25
	v_fmac_f32_e32 v6, v32, v29
	s_waitcnt vmcnt(1)
	v_fmac_f32_e32 v4, v33, v22
	v_fmac_f32_e32 v5, v33, v26
	v_fmac_f32_e32 v6, v33, v30
	s_waitcnt vmcnt(0)
	v_fmac_f32_e32 v4, v2, v23
	v_fmac_f32_e32 v5, v2, v27
	v_fmac_f32_e32 v6, v2, v31
	ds_write_b32 v105, v4 offset:12288
	ds_write_b32 v109, v5 offset:14336
	ds_write_b32 v105, v6 offset:16384
	s_waitcnt lgkmcnt(0)
	s_barrier
	s_and_saveexec_b64 s[14:15], s[6:7]
	s_cbranch_execz .LBB0_50
	s_load_dwordx16 s[36:51], s[0:1], 0x0
	v_or_b32_e32 v54, s30, v107
	v_add_u32_e32 v8, 0x3000, v110
	v_add_u32_e32 v16, 0x3400, v110
	s_waitcnt lgkmcnt(0)
	v_lshl_add_u64 v[2:3], v[54:55], 2, s[48:49]
	global_load_dword v18, v[2:3], off nt
	ds_read2_b32 v[2:3], v8 offset1:32
	ds_read2_b32 v[4:5], v8 offset0:64 offset1:96
	ds_read2_b32 v[6:7], v8 offset0:128 offset1:160
	ds_read2_b32 v[8:9], v8 offset0:192 offset1:224
	ds_read2_b32 v[10:11], v16 offset1:32
	ds_read2_b32 v[12:13], v16 offset0:64 offset1:96
	ds_read2_b32 v[14:15], v16 offset0:128 offset1:160
	ds_read2_b32 v[16:17], v16 offset0:192 offset1:224
	v_add_u32_e32 v54, s30, v111
	s_waitcnt vmcnt(0) lgkmcnt(7)
	v_add_f32_e32 v2, v18, v2
	v_add_f32_e32 v2, v2, v3
	s_waitcnt lgkmcnt(6)
	v_add_f32_e32 v2, v2, v4
	v_add_f32_e32 v2, v2, v5
	s_waitcnt lgkmcnt(5)
	v_add_f32_e32 v2, v2, v6
	v_add_f32_e32 v2, v2, v7
	s_waitcnt lgkmcnt(4)
	v_add_f32_e32 v2, v2, v8
	v_add_f32_e32 v2, v2, v9
	s_waitcnt lgkmcnt(3)
	v_add_f32_e32 v2, v2, v10
	v_add_f32_e32 v2, v2, v11
	s_waitcnt lgkmcnt(2)
	v_add_f32_e32 v2, v2, v12
	v_add_f32_e32 v2, v2, v13
	s_waitcnt lgkmcnt(1)
	v_add_f32_e32 v2, v2, v14
	v_add_f32_e32 v2, v2, v15
	s_waitcnt lgkmcnt(0)
	v_add_f32_e32 v2, v2, v16
	v_add_f32_e32 v4, v2, v17
	v_lshl_add_u64 v[2:3], v[54:55], 2, s[72:73]
	global_store_dword v[2:3], v4, off
